# stack4 + P7: XC pieces for the scan epilogue requested before the K-loop's last MFMA segment (addresses formed in the load segment), epilogue copies instead of loads
# baseline (speedup 1.0000x reference)
.LBB0_861:
	s_add_u32 s80, s74, 0x8000
	ds_read_b128 v[2:5], v222
	ds_read_b128 v[6:9], v222 offset:1024
	ds_read_b128 v[10:13], v222 offset:2048
	ds_read_b128 v[14:17], v222 offset:3072
	ds_read_b128 v[18:21], v223
	ds_read_b128 v[22:25], v223 offset:1024
	ds_read_b128 v[26:29], v223 offset:2048
	ds_read_b128 v[30:33], v223 offset:3072
	s_addc_u32 s81, s75, 0
	s_add_u32 s78, s14, 0x8000
	s_addc_u32 s79, s15, 0
	s_add_u32 s84, s76, 0x8000
	s_addc_u32 s85, s77, 0
	s_add_u32 s82, s72, 0x8000
	s_addc_u32 s83, s73, 0
	s_add_u32 s76, s76, 0xc000
	s_addc_u32 s77, s77, 0
	s_add_u32 s74, s74, 0xc000
	s_addc_u32 s75, s75, 0
	s_add_u32 s86, s14, 0x4000
	s_addc_u32 s87, s15, 0
	s_add_i32 vcc_lo, s17, 0xc000
	ds_read_b128 v[34:37], v224
	ds_read_b128 v[38:41], v224 offset:1024
	ds_read_b128 v[42:45], v224 offset:2048
	ds_read_b128 v[46:49], v224 offset:3072
	ds_read_b128 v[50:53], v224 offset:4096
	ds_read_b128 v[54:57], v224 offset:5120
	ds_read_b128 v[58:61], v224 offset:6144
	ds_read_b128 v[62:65], v224 offset:7168
	s_mov_b32 m0, vcc_lo
	v_lshl_add_u64 v[66:67], s[86:87], 0, v[152:153]
	s_add_i32 s48, s17, 0xe000
	global_load_lds_dwordx4 v[66:67], off
	v_lshl_add_u64 v[66:67], v[66:67], 0, s[50:51]
	s_mov_b32 m0, s48
	s_nop 0
	global_load_lds_dwordx4 v[66:67], off
	s_waitcnt vmcnt(8)
	s_waitcnt lgkmcnt(0)
	s_barrier
	s_setprio 1
	s_waitcnt lgkmcnt(0)
	v_mfma_f32_16x16x32_bf16 v[66:69], v[2:5], v[34:37], 0
	v_mfma_f32_16x16x32_bf16 v[70:73], v[10:13], v[34:37], 0
	v_mfma_f32_16x16x32_bf16 v[74:77], v[2:5], v[42:45], 0
	v_mfma_f32_16x16x32_bf16 v[78:81], v[10:13], v[42:45], 0
	v_mfma_f32_16x16x32_bf16 v[82:85], v[2:5], v[50:53], 0
	v_mfma_f32_16x16x32_bf16 v[86:89], v[10:13], v[50:53], 0
	v_mfma_f32_16x16x32_bf16 v[66:69], v[6:9], v[38:41], v[66:69]
	v_mfma_f32_16x16x32_bf16 v[70:73], v[14:17], v[38:41], v[70:73]
	v_mfma_f32_16x16x32_bf16 v[74:77], v[6:9], v[46:49], v[74:77]
	v_mfma_f32_16x16x32_bf16 v[78:81], v[14:17], v[46:49], v[78:81]
	v_mfma_f32_16x16x32_bf16 v[82:85], v[6:9], v[54:57], v[82:85]
	v_mfma_f32_16x16x32_bf16 v[86:89], v[14:17], v[54:57], v[86:89]
	v_mfma_f32_16x16x32_bf16 v[90:93], v[2:5], v[58:61], 0
	v_mfma_f32_16x16x32_bf16 v[94:97], v[10:13], v[58:61], 0
	v_mfma_f32_16x16x32_bf16 v[90:93], v[6:9], v[62:65], v[90:93]
	v_mfma_f32_16x16x32_bf16 v[94:97], v[14:17], v[62:65], v[94:97]
	s_setprio 0
	s_setprio 1
	v_mfma_f32_16x16x32_bf16 v[98:101], v[18:21], v[34:37], 0
	v_mfma_f32_16x16x32_bf16 v[34:37], v[26:29], v[34:37], 0
	v_mfma_f32_16x16x32_bf16 v[98:101], v[22:25], v[38:41], v[98:101]
	v_mfma_f32_16x16x32_bf16 v[34:37], v[30:33], v[38:41], v[34:37]
	v_mfma_f32_16x16x32_bf16 v[38:41], v[18:21], v[42:45], 0
	v_mfma_f32_16x16x32_bf16 v[42:45], v[26:29], v[42:45], 0
	v_mfma_f32_16x16x32_bf16 v[38:41], v[22:25], v[46:49], v[38:41]
	v_mfma_f32_16x16x32_bf16 v[42:45], v[30:33], v[46:49], v[42:45]
	v_mfma_f32_16x16x32_bf16 v[46:49], v[18:21], v[50:53], 0
	v_mfma_f32_16x16x32_bf16 v[50:53], v[26:29], v[50:53], 0
	v_mfma_f32_16x16x32_bf16 v[46:49], v[22:25], v[54:57], v[46:49]
	v_mfma_f32_16x16x32_bf16 v[50:53], v[30:33], v[54:57], v[50:53]
	v_mfma_f32_16x16x32_bf16 v[54:57], v[18:21], v[58:61], 0
	v_mfma_f32_16x16x32_bf16 v[58:61], v[26:29], v[58:61], 0
	v_mfma_f32_16x16x32_bf16 v[54:57], v[22:25], v[62:65], v[54:57]
	v_mfma_f32_16x16x32_bf16 v[58:61], v[30:33], v[62:65], v[58:61]
	s_setprio 0
	s_barrier
	ds_read_b128 v[62:65], v224 offset:16384
	ds_read_b128 v[102:105], v224 offset:17408
	ds_read_b128 v[106:109], v224 offset:18432
	ds_read_b128 v[110:113], v224 offset:19456
	ds_read_b128 v[114:117], v224 offset:20480
	ds_read_b128 v[118:121], v224 offset:21504
	ds_read_b128 v[122:125], v224 offset:22528
	ds_read_b128 v[126:129], v224 offset:23552
	s_nop 0
	v_lshl_add_u64 v[130:131], s[84:85], 0, v[152:153]
	s_add_i32 s85, s94, s16
	s_mov_b32 m0, s85
	s_add_i32 s84, s85, 0x2000
	global_load_lds_dwordx4 v[130:131], off
	v_lshl_add_u64 v[130:131], v[130:131], 0, s[50:51]
	s_mov_b32 m0, s84
	s_nop 0
	global_load_lds_dwordx4 v[130:131], off
	s_nop 0
	v_lshl_add_u64 v[130:131], s[82:83], 0, v[152:153]
	s_add_i32 s82, s95, s16
	s_mov_b32 m0, s82
	s_add_i32 s83, s82, 0x2000
	global_load_lds_dwordx4 v[130:131], off
	v_lshl_add_u64 v[130:131], v[130:131], 0, s[50:51]
	s_mov_b32 m0, s83
	s_nop 0
	global_load_lds_dwordx4 v[130:131], off
	s_mov_b32 m0, s17
	v_lshl_add_u64 v[130:131], s[80:81], 0, v[152:153]
	global_load_lds_dwordx4 v[130:131], off
	v_lshl_add_u64 v[130:131], v[130:131], 0, s[50:51]
	s_mov_b32 m0, s22
	s_nop 0
	global_load_lds_dwordx4 v[130:131], off
	s_waitcnt vmcnt(8)
	s_waitcnt lgkmcnt(0)
	s_barrier
	s_setprio 1
	s_waitcnt lgkmcnt(0)
	v_mfma_f32_16x16x32_bf16 v[130:133], v[2:5], v[62:65], 0
	v_mfma_f32_16x16x32_bf16 v[138:141], v[2:5], v[106:109], 0
	v_mfma_f32_16x16x32_bf16 v[146:149], v[2:5], v[114:117], 0
	v_mfma_f32_16x16x32_bf16 v[2:5], v[2:5], v[122:125], 0
	v_mfma_f32_16x16x32_bf16 v[130:133], v[6:9], v[102:105], v[130:133]
	v_mfma_f32_16x16x32_bf16 v[138:141], v[6:9], v[110:113], v[138:141]
	v_mfma_f32_16x16x32_bf16 v[142:145], v[10:13], v[106:109], 0
	v_mfma_f32_16x16x32_bf16 v[146:149], v[6:9], v[118:121], v[146:149]
	v_mfma_f32_16x16x32_bf16 v[2:5], v[6:9], v[126:129], v[2:5]
	v_mfma_f32_16x16x32_bf16 v[6:9], v[10:13], v[122:125], 0
	v_mfma_f32_16x16x32_bf16 v[134:137], v[10:13], v[62:65], 0
	v_mfma_f32_16x16x32_bf16 v[142:145], v[14:17], v[110:113], v[142:145]
	v_mfma_f32_16x16x32_bf16 v[156:159], v[10:13], v[114:117], 0
	v_mfma_f32_16x16x32_bf16 v[6:9], v[14:17], v[126:129], v[6:9]
	v_mfma_f32_16x16x32_bf16 v[134:137], v[14:17], v[102:105], v[134:137]
	v_mfma_f32_16x16x32_bf16 v[156:159], v[14:17], v[118:121], v[156:159]
	s_setprio 0
	s_setprio 1
	v_mfma_f32_16x16x32_bf16 v[10:13], v[18:21], v[62:65], 0
	v_mfma_f32_16x16x32_bf16 v[14:17], v[26:29], v[62:65], 0
	v_mfma_f32_16x16x32_bf16 v[10:13], v[22:25], v[102:105], v[10:13]
	v_mfma_f32_16x16x32_bf16 v[14:17], v[30:33], v[102:105], v[14:17]
	v_mfma_f32_16x16x32_bf16 v[62:65], v[18:21], v[106:109], 0
	v_mfma_f32_16x16x32_bf16 v[102:105], v[26:29], v[106:109], 0
	v_mfma_f32_16x16x32_bf16 v[106:109], v[18:21], v[114:117], 0
	v_mfma_f32_16x16x32_bf16 v[18:21], v[18:21], v[122:125], 0
	v_mfma_f32_16x16x32_bf16 v[62:65], v[22:25], v[110:113], v[62:65]
	v_mfma_f32_16x16x32_bf16 v[102:105], v[30:33], v[110:113], v[102:105]
	v_mfma_f32_16x16x32_bf16 v[106:109], v[22:25], v[118:121], v[106:109]
	v_mfma_f32_16x16x32_bf16 v[110:113], v[26:29], v[114:117], 0
	v_mfma_f32_16x16x32_bf16 v[18:21], v[22:25], v[126:129], v[18:21]
	v_mfma_f32_16x16x32_bf16 v[22:25], v[26:29], v[122:125], 0
	v_mfma_f32_16x16x32_bf16 v[110:113], v[30:33], v[118:121], v[110:113]
	v_mfma_f32_16x16x32_bf16 v[22:25], v[30:33], v[126:129], v[22:25]
	s_setprio 0
	s_barrier
	s_add_i32 s80, 0, 0x18000
	s_add_i32 s81, 0, 0x1c000
	v_add_u32_e32 v154, s80, v221
	v_add_u32_e32 v225, s81, v221
	ds_read_b128 v[26:29], v154
	ds_read_b128 v[30:33], v154 offset:1024
	ds_read_b128 v[114:117], v154 offset:2048
	ds_read_b128 v[118:121], v154 offset:3072
	ds_read_b128 v[122:125], v225
	ds_read_b128 v[126:129], v225 offset:1024
	ds_read_b128 v[160:163], v225 offset:2048
	ds_read_b128 v[164:167], v225 offset:3072
	s_mov_b32 m0, s23
	ds_read_b128 v[168:171], v224 offset:32768
	ds_read_b128 v[172:175], v224 offset:33792
	ds_read_b128 v[176:179], v224 offset:34816
	ds_read_b128 v[180:183], v224 offset:35840
	ds_read_b128 v[184:187], v224 offset:36864
	ds_read_b128 v[188:191], v224 offset:37888
	ds_read_b128 v[192:195], v224 offset:38912
	ds_read_b128 v[196:199], v224 offset:39936
	s_nop 0
	v_lshl_add_u64 v[150:151], s[78:79], 0, v[152:153]
	global_load_lds_dwordx4 v[150:151], off
	v_lshl_add_u64 v[150:151], v[150:151], 0, s[50:51]
	s_mov_b32 m0, s24
	s_nop 0
	global_load_lds_dwordx4 v[150:151], off
	s_waitcnt vmcnt(8)
	s_waitcnt lgkmcnt(0)
	s_barrier
	s_setprio 1
	s_waitcnt lgkmcnt(0)
	v_mfma_f32_16x16x32_bf16 v[66:69], v[26:29], v[168:171], v[66:69]
	v_mfma_f32_16x16x32_bf16 v[70:73], v[114:117], v[168:171], v[70:73]
	v_mfma_f32_16x16x32_bf16 v[74:77], v[26:29], v[176:179], v[74:77]
	v_mfma_f32_16x16x32_bf16 v[78:81], v[114:117], v[176:179], v[78:81]
	v_mfma_f32_16x16x32_bf16 v[82:85], v[26:29], v[184:187], v[82:85]
	v_mfma_f32_16x16x32_bf16 v[86:89], v[114:117], v[184:187], v[86:89]
	v_mfma_f32_16x16x32_bf16 v[66:69], v[30:33], v[172:175], v[66:69]
	v_mfma_f32_16x16x32_bf16 v[70:73], v[118:121], v[172:175], v[70:73]
	v_mfma_f32_16x16x32_bf16 v[74:77], v[30:33], v[180:183], v[74:77]
	v_mfma_f32_16x16x32_bf16 v[78:81], v[118:121], v[180:183], v[78:81]
	v_mfma_f32_16x16x32_bf16 v[82:85], v[30:33], v[188:191], v[82:85]
	v_mfma_f32_16x16x32_bf16 v[86:89], v[118:121], v[188:191], v[86:89]
	v_mfma_f32_16x16x32_bf16 v[90:93], v[26:29], v[192:195], v[90:93]
	v_mfma_f32_16x16x32_bf16 v[94:97], v[114:117], v[192:195], v[94:97]
	v_mfma_f32_16x16x32_bf16 v[90:93], v[30:33], v[196:199], v[90:93]
	v_mfma_f32_16x16x32_bf16 v[94:97], v[118:121], v[196:199], v[94:97]
	s_setprio 0
	s_setprio 1
	v_mfma_f32_16x16x32_bf16 v[98:101], v[122:125], v[168:171], v[98:101]
	v_mfma_f32_16x16x32_bf16 v[34:37], v[160:163], v[168:171], v[34:37]
	v_mfma_f32_16x16x32_bf16 v[38:41], v[122:125], v[176:179], v[38:41]
	v_mfma_f32_16x16x32_bf16 v[42:45], v[160:163], v[176:179], v[42:45]
	v_mfma_f32_16x16x32_bf16 v[46:49], v[122:125], v[184:187], v[46:49]
	v_mfma_f32_16x16x32_bf16 v[50:53], v[160:163], v[184:187], v[50:53]
	v_mfma_f32_16x16x32_bf16 v[54:57], v[122:125], v[192:195], v[54:57]
	v_mfma_f32_16x16x32_bf16 v[58:61], v[160:163], v[192:195], v[58:61]
	v_mfma_f32_16x16x32_bf16 v[98:101], v[126:129], v[172:175], v[98:101]
	v_mfma_f32_16x16x32_bf16 v[34:37], v[164:167], v[172:175], v[34:37]
	v_mfma_f32_16x16x32_bf16 v[38:41], v[126:129], v[180:183], v[38:41]
	v_mfma_f32_16x16x32_bf16 v[42:45], v[164:167], v[180:183], v[42:45]
	v_mfma_f32_16x16x32_bf16 v[46:49], v[126:129], v[188:191], v[46:49]
	v_mfma_f32_16x16x32_bf16 v[50:53], v[164:167], v[188:191], v[50:53]
	v_mfma_f32_16x16x32_bf16 v[54:57], v[126:129], v[196:199], v[54:57]
	v_mfma_f32_16x16x32_bf16 v[58:61], v[164:167], v[196:199], v[58:61]
	s_setprio 0
	s_barrier
	ds_read_b128 v[168:171], v224 offset:49152
	ds_read_b128 v[172:175], v224 offset:50176
	ds_read_b128 v[176:179], v224 offset:51200
	ds_read_b128 v[180:183], v224 offset:52224
	ds_read_b128 v[184:187], v224 offset:53248
	ds_read_b128 v[188:191], v224 offset:54272
	ds_read_b128 v[192:195], v224 offset:55296
	ds_read_b128 v[196:199], v224 offset:56320
	s_add_i32 s79, s80, s16
	v_lshl_add_u64 v[150:151], s[76:77], 0, v[152:153]
	s_add_i32 s76, s79, 0x2000
	s_mov_b32 m0, s79
	s_add_u32 s72, s72, 0xc000
	global_load_lds_dwordx4 v[150:151], off
	v_lshl_add_u64 v[150:151], v[150:151], 0, s[50:51]
	s_mov_b32 m0, s76
	s_addc_u32 s73, s73, 0
	s_add_i32 s77, s81, s16
	global_load_lds_dwordx4 v[150:151], off
	s_mov_b32 m0, s77
	v_lshl_add_u64 v[150:151], s[72:73], 0, v[152:153]
	s_add_i32 s78, s77, 0x2000
	global_load_lds_dwordx4 v[150:151], off
	v_lshl_add_u64 v[150:151], v[150:151], 0, s[50:51]
	s_mov_b32 m0, s78
	s_nop 0
	global_load_lds_dwordx4 v[150:151], off
	s_mov_b32 m0, s31
	v_lshl_add_u64 v[150:151], s[74:75], 0, v[152:153]
	global_load_lds_dwordx4 v[150:151], off
	v_lshl_add_u64 v[150:151], v[150:151], 0, s[50:51]
	s_mov_b32 m0, s33
	s_nop 0
	global_load_lds_dwordx4 v[150:151], off
	s_waitcnt vmcnt(8)
	s_waitcnt lgkmcnt(0)
	s_barrier
	s_setprio 1
	s_waitcnt lgkmcnt(0)
	v_mfma_f32_16x16x32_bf16 v[142:145], v[114:117], v[176:179], v[142:145]
	v_mfma_f32_16x16x32_bf16 v[146:149], v[26:29], v[184:187], v[146:149]
	v_mfma_f32_16x16x32_bf16 v[2:5], v[26:29], v[192:195], v[2:5]
	v_mfma_f32_16x16x32_bf16 v[6:9], v[114:117], v[192:195], v[6:9]
	v_mfma_f32_16x16x32_bf16 v[130:133], v[26:29], v[168:171], v[130:133]
	v_mfma_f32_16x16x32_bf16 v[134:137], v[114:117], v[168:171], v[134:137]
	v_mfma_f32_16x16x32_bf16 v[138:141], v[26:29], v[176:179], v[138:141]
	v_mfma_f32_16x16x32_bf16 v[142:145], v[118:121], v[180:183], v[142:145]
	v_mfma_f32_16x16x32_bf16 v[146:149], v[30:33], v[188:191], v[146:149]
	v_mfma_f32_16x16x32_bf16 v[156:159], v[114:117], v[184:187], v[156:159]
	v_mfma_f32_16x16x32_bf16 v[2:5], v[30:33], v[196:199], v[2:5]
	v_mfma_f32_16x16x32_bf16 v[6:9], v[118:121], v[196:199], v[6:9]
	v_mfma_f32_16x16x32_bf16 v[130:133], v[30:33], v[172:175], v[130:133]
	v_mfma_f32_16x16x32_bf16 v[134:137], v[118:121], v[172:175], v[134:137]
	v_mfma_f32_16x16x32_bf16 v[138:141], v[30:33], v[180:183], v[138:141]
	v_mfma_f32_16x16x32_bf16 v[156:159], v[118:121], v[188:191], v[156:159]
	s_setprio 0
	s_setprio 1
	v_mfma_f32_16x16x32_bf16 v[10:13], v[122:125], v[168:171], v[10:13]
	v_mfma_f32_16x16x32_bf16 v[14:17], v[160:163], v[168:171], v[14:17]
	v_mfma_f32_16x16x32_bf16 v[26:29], v[122:125], v[176:179], v[62:65]
	v_mfma_f32_16x16x32_bf16 v[30:33], v[160:163], v[176:179], v[102:105]
	v_mfma_f32_16x16x32_bf16 v[62:65], v[122:125], v[184:187], v[106:109]
	v_mfma_f32_16x16x32_bf16 v[102:105], v[160:163], v[184:187], v[110:113]
	v_mfma_f32_16x16x32_bf16 v[18:21], v[122:125], v[192:195], v[18:21]
	v_mfma_f32_16x16x32_bf16 v[22:25], v[160:163], v[192:195], v[22:25]
	v_mfma_f32_16x16x32_bf16 v[10:13], v[126:129], v[172:175], v[10:13]
	v_mfma_f32_16x16x32_bf16 v[14:17], v[164:167], v[172:175], v[14:17]
	v_mfma_f32_16x16x32_bf16 v[26:29], v[126:129], v[180:183], v[26:29]
	v_mfma_f32_16x16x32_bf16 v[30:33], v[164:167], v[180:183], v[30:33]
	v_mfma_f32_16x16x32_bf16 v[62:65], v[126:129], v[188:191], v[62:65]
	v_mfma_f32_16x16x32_bf16 v[102:105], v[164:167], v[188:191], v[102:105]
	v_mfma_f32_16x16x32_bf16 v[18:21], v[126:129], v[196:199], v[18:21]
	v_mfma_f32_16x16x32_bf16 v[22:25], v[164:167], v[196:199], v[22:25]
	s_setprio 0
	s_barrier
	ds_read_b128 v[106:109], v222
	ds_read_b128 v[110:113], v222 offset:1024
	ds_read_b128 v[114:117], v222 offset:2048
	ds_read_b128 v[118:121], v222 offset:3072
	ds_read_b128 v[122:125], v223
	ds_read_b128 v[126:129], v223 offset:1024
	ds_read_b128 v[160:163], v223 offset:2048
	ds_read_b128 v[164:167], v223 offset:3072
	s_add_u32 s74, s68, 0x4000
	s_addc_u32 s75, s69, 0
	s_add_u32 s72, s64, 0x4000
	s_addc_u32 s73, s65, 0
	s_add_u32 s14, s14, 0xc000
	s_addc_u32 s15, s15, 0
	s_mov_b32 m0, vcc_lo
	ds_read_b128 v[168:171], v224
	ds_read_b128 v[172:175], v224 offset:1024
	ds_read_b128 v[176:179], v224 offset:2048
	ds_read_b128 v[180:183], v224 offset:3072
	ds_read_b128 v[184:187], v224 offset:4096
	ds_read_b128 v[188:191], v224 offset:5120
	ds_read_b128 v[192:195], v224 offset:6144
	ds_read_b128 v[196:199], v224 offset:7168
	s_nop 0
	v_lshl_add_u64 v[150:151], s[14:15], 0, v[152:153]
	global_load_lds_dwordx4 v[150:151], off
	v_lshl_add_u64 v[150:151], v[150:151], 0, s[50:51]
	s_mov_b32 m0, s48
	s_nop 0
	global_load_lds_dwordx4 v[150:151], off
	s_waitcnt vmcnt(8)
	s_waitcnt lgkmcnt(0)
	s_barrier
	s_setprio 1
	s_waitcnt lgkmcnt(0)
	v_mfma_f32_16x16x32_bf16 v[86:89], v[114:117], v[184:187], v[86:89]
	v_mfma_f32_16x16x32_bf16 v[66:69], v[106:109], v[168:171], v[66:69]
	v_mfma_f32_16x16x32_bf16 v[70:73], v[114:117], v[168:171], v[70:73]
	v_mfma_f32_16x16x32_bf16 v[74:77], v[106:109], v[176:179], v[74:77]
	v_mfma_f32_16x16x32_bf16 v[78:81], v[114:117], v[176:179], v[78:81]
	v_mfma_f32_16x16x32_bf16 v[82:85], v[106:109], v[184:187], v[82:85]
	v_mfma_f32_16x16x32_bf16 v[200:203], v[118:121], v[188:191], v[86:89]
	v_mfma_f32_16x16x32_bf16 v[86:89], v[106:109], v[192:195], v[90:93]
	v_mfma_f32_16x16x32_bf16 v[66:69], v[110:113], v[172:175], v[66:69]
	v_mfma_f32_16x16x32_bf16 v[70:73], v[118:121], v[172:175], v[70:73]
	v_mfma_f32_16x16x32_bf16 v[74:77], v[110:113], v[180:183], v[74:77]
	v_mfma_f32_16x16x32_bf16 v[78:81], v[118:121], v[180:183], v[78:81]
	v_mfma_f32_16x16x32_bf16 v[82:85], v[110:113], v[188:191], v[82:85]
	v_mfma_f32_16x16x32_bf16 v[90:93], v[110:113], v[196:199], v[86:89]
	v_mfma_f32_16x16x32_bf16 v[86:89], v[114:117], v[192:195], v[94:97]
	v_mfma_f32_16x16x32_bf16 v[94:97], v[118:121], v[196:199], v[86:89]
	s_setprio 0
	s_setprio 1
	v_mfma_f32_16x16x32_bf16 v[50:53], v[160:163], v[184:187], v[50:53]
	v_mfma_f32_16x16x32_bf16 v[86:89], v[122:125], v[168:171], v[98:101]
	v_mfma_f32_16x16x32_bf16 v[34:37], v[160:163], v[168:171], v[34:37]
	v_mfma_f32_16x16x32_bf16 v[38:41], v[122:125], v[176:179], v[38:41]
	v_mfma_f32_16x16x32_bf16 v[42:45], v[160:163], v[176:179], v[42:45]
	v_mfma_f32_16x16x32_bf16 v[46:49], v[122:125], v[184:187], v[46:49]
	v_mfma_f32_16x16x32_bf16 v[168:171], v[164:167], v[188:191], v[50:53]
	v_mfma_f32_16x16x32_bf16 v[50:53], v[122:125], v[192:195], v[54:57]
	v_mfma_f32_16x16x32_bf16 v[98:101], v[126:129], v[172:175], v[86:89]
	v_mfma_f32_16x16x32_bf16 v[34:37], v[164:167], v[172:175], v[34:37]
	v_mfma_f32_16x16x32_bf16 v[38:41], v[126:129], v[180:183], v[38:41]
	v_mfma_f32_16x16x32_bf16 v[42:45], v[164:167], v[180:183], v[42:45]
	v_mfma_f32_16x16x32_bf16 v[46:49], v[126:129], v[188:191], v[46:49]
	v_mfma_f32_16x16x32_bf16 v[172:175], v[126:129], v[196:199], v[50:53]
	v_mfma_f32_16x16x32_bf16 v[50:53], v[160:163], v[192:195], v[58:61]
	v_mfma_f32_16x16x32_bf16 v[176:179], v[164:167], v[196:199], v[50:53]
	s_setprio 0
	s_barrier
	s_mov_b64 s[14:15], s[68:69]
	s_mov_b32 m0, s85
	s_nop 2
	ds_read_b128 v[50:53], v224 offset:16384
	ds_read_b128 v[54:57], v224 offset:17408
	ds_read_b128 v[58:61], v224 offset:18432
	ds_read_b128 v[86:89], v224 offset:19456
	ds_read_b128 v[180:183], v224 offset:20480
	ds_read_b128 v[184:187], v224 offset:21504
	ds_read_b128 v[188:191], v224 offset:22528
	ds_read_b128 v[192:195], v224 offset:23552
	s_nop 0
	v_lshl_add_u64 v[150:151], s[14:15], 0, v[152:153]
	global_load_lds_dwordx4 v[150:151], off
	v_lshl_add_u64 v[150:151], v[150:151], 0, s[50:51]
	s_mov_b32 m0, s84
	s_mov_b64 s[14:15], s[70:71]
	global_load_lds_dwordx4 v[150:151], off
	s_mov_b32 m0, s82
	v_lshl_add_u64 v[150:151], s[14:15], 0, v[152:153]
	global_load_lds_dwordx4 v[150:151], off
	v_lshl_add_u64 v[150:151], v[150:151], 0, s[50:51]
	s_mov_b32 m0, s83
	s_mov_b64 s[14:15], s[64:65]
	global_load_lds_dwordx4 v[150:151], off
	s_mov_b32 m0, s17
	v_lshl_add_u64 v[150:151], s[14:15], 0, v[152:153]
	global_load_lds_dwordx4 v[150:151], off
	v_lshl_add_u64 v[150:151], v[150:151], 0, s[50:51]
	s_mov_b32 m0, s22
	s_nop 0
	global_load_lds_dwordx4 v[150:151], off
	s_waitcnt vmcnt(8)
	s_waitcnt lgkmcnt(0)
	s_barrier
	s_setprio 1
	s_waitcnt lgkmcnt(0)
	v_mfma_f32_16x16x32_bf16 v[142:145], v[114:117], v[58:61], v[142:145]
	v_mfma_f32_16x16x32_bf16 v[196:199], v[118:121], v[86:89], v[142:145]
	v_mfma_f32_16x16x32_bf16 v[142:145], v[106:109], v[180:183], v[146:149]
	v_mfma_f32_16x16x32_bf16 v[2:5], v[106:109], v[188:191], v[2:5]
	v_mfma_f32_16x16x32_bf16 v[6:9], v[114:117], v[188:191], v[6:9]
	v_mfma_f32_16x16x32_bf16 v[130:133], v[106:109], v[50:53], v[130:133]
	v_mfma_f32_16x16x32_bf16 v[134:137], v[114:117], v[50:53], v[134:137]
	v_mfma_f32_16x16x32_bf16 v[138:141], v[106:109], v[58:61], v[138:141]
	v_mfma_f32_16x16x32_bf16 v[204:207], v[110:113], v[184:187], v[142:145]
	v_mfma_f32_16x16x32_bf16 v[142:145], v[114:117], v[180:183], v[156:159]
	v_mfma_f32_16x16x32_bf16 v[2:5], v[110:113], v[192:195], v[2:5]
	v_mfma_f32_16x16x32_bf16 v[6:9], v[118:121], v[192:195], v[6:9]
	v_mfma_f32_16x16x32_bf16 v[130:133], v[110:113], v[54:57], v[130:133]
	v_mfma_f32_16x16x32_bf16 v[134:137], v[118:121], v[54:57], v[134:137]
	v_mfma_f32_16x16x32_bf16 v[138:141], v[110:113], v[86:89], v[138:141]
	v_mfma_f32_16x16x32_bf16 v[156:159], v[118:121], v[184:187], v[142:145]
	s_setprio 0
	s_setprio 1
	v_mfma_f32_16x16x32_bf16 v[26:29], v[122:125], v[58:61], v[26:29]
	v_mfma_f32_16x16x32_bf16 v[208:211], v[126:129], v[86:89], v[26:29]
	v_mfma_f32_16x16x32_bf16 v[26:29], v[160:163], v[58:61], v[30:33]
	v_mfma_f32_16x16x32_bf16 v[212:215], v[164:167], v[86:89], v[26:29]
	v_mfma_f32_16x16x32_bf16 v[26:29], v[122:125], v[180:183], v[62:65]
	v_mfma_f32_16x16x32_bf16 v[10:13], v[122:125], v[50:53], v[10:13]
	v_mfma_f32_16x16x32_bf16 v[14:17], v[160:163], v[50:53], v[14:17]
	v_mfma_f32_16x16x32_bf16 v[216:219], v[126:129], v[184:187], v[26:29]
	v_mfma_f32_16x16x32_bf16 v[26:29], v[160:163], v[180:183], v[102:105]
	v_mfma_f32_16x16x32_bf16 v[18:21], v[122:125], v[188:191], v[18:21]
	v_mfma_f32_16x16x32_bf16 v[10:13], v[126:129], v[54:57], v[10:13]
	v_mfma_f32_16x16x32_bf16 v[14:17], v[164:167], v[54:57], v[14:17]
	v_mfma_f32_16x16x32_bf16 v[180:183], v[164:167], v[184:187], v[26:29]
	v_mfma_f32_16x16x32_bf16 v[184:187], v[126:129], v[192:195], v[18:21]
	v_mfma_f32_16x16x32_bf16 v[18:21], v[160:163], v[188:191], v[22:25]
	v_mfma_f32_16x16x32_bf16 v[160:163], v[164:167], v[192:195], v[18:21]
	s_setprio 0
	s_barrier
	s_nop 4
	ds_read_b128 v[18:21], v154
	ds_read_b128 v[22:25], v154 offset:1024
	ds_read_b128 v[26:29], v154 offset:2048
	ds_read_b128 v[30:33], v154 offset:3072
	ds_read_b128 v[164:167], v225
	ds_read_b128 v[188:191], v225 offset:1024
	ds_read_b128 v[192:195], v225 offset:2048
	ds_read_b128 v[226:229], v225 offset:3072
	s_mov_b64 s[14:15], s[66:67]
	s_mov_b32 m0, s23
	ds_read_b128 v[54:57], v224 offset:32768
	ds_read_b128 v[58:61], v224 offset:33792
	ds_read_b128 v[102:105], v224 offset:34816
	ds_read_b128 v[106:109], v224 offset:35840
	ds_read_b128 v[110:113], v224 offset:36864
	ds_read_b128 v[114:117], v224 offset:37888
	ds_read_b128 v[118:121], v224 offset:38912
	ds_read_b128 v[230:233], v224 offset:39936
	s_nop 0
	v_lshl_add_u64 v[50:51], s[14:15], 0, v[152:153]
	global_load_lds_dwordx4 v[50:51], off
	v_lshl_add_u64 v[50:51], v[50:51], 0, s[50:51]
	s_mov_b32 m0, s24
	s_nop 0
	global_load_lds_dwordx4 v[50:51], off
	s_waitcnt vmcnt(8)
	s_waitcnt lgkmcnt(0)
	s_barrier
	s_setprio 1
	s_waitcnt lgkmcnt(0)
	v_mfma_f32_16x16x32_bf16 v[50:53], v[18:21], v[54:57], v[66:69]
	v_mfma_f32_16x16x32_bf16 v[146:149], v[22:25], v[58:61], v[50:53]
	v_mfma_f32_16x16x32_bf16 v[50:53], v[26:29], v[54:57], v[70:73]
	v_mfma_f32_16x16x32_bf16 v[142:145], v[30:33], v[58:61], v[50:53]
	v_mfma_f32_16x16x32_bf16 v[50:53], v[18:21], v[102:105], v[74:77]
	v_mfma_f32_16x16x32_bf16 v[126:129], v[22:25], v[106:109], v[50:53]
	v_mfma_f32_16x16x32_bf16 v[50:53], v[26:29], v[102:105], v[78:81]
	v_mfma_f32_16x16x32_bf16 v[122:125], v[30:33], v[106:109], v[50:53]
	v_mfma_f32_16x16x32_bf16 v[50:53], v[18:21], v[110:113], v[82:85]
	v_mfma_f32_16x16x32_bf16 v[86:89], v[22:25], v[114:117], v[50:53]
	v_mfma_f32_16x16x32_bf16 v[50:53], v[26:29], v[110:113], v[200:203]
	v_mfma_f32_16x16x32_bf16 v[74:77], v[30:33], v[114:117], v[50:53]
	v_mfma_f32_16x16x32_bf16 v[50:53], v[18:21], v[118:121], v[90:93]
	v_mfma_f32_16x16x32_bf16 v[70:73], v[22:25], v[230:233], v[50:53]
	v_mfma_f32_16x16x32_bf16 v[50:53], v[26:29], v[118:121], v[94:97]
	v_mfma_f32_16x16x32_bf16 v[50:53], v[30:33], v[230:233], v[50:53]
	s_setprio 0
	s_setprio 1
	v_mfma_f32_16x16x32_bf16 v[62:65], v[164:167], v[54:57], v[98:101]
	v_mfma_f32_16x16x32_bf16 v[34:37], v[192:195], v[54:57], v[34:37]
	v_mfma_f32_16x16x32_bf16 v[66:69], v[188:191], v[58:61], v[62:65]
	v_mfma_f32_16x16x32_bf16 v[62:65], v[226:229], v[58:61], v[34:37]
	v_mfma_f32_16x16x32_bf16 v[34:37], v[164:167], v[102:105], v[38:41]
	v_mfma_f32_16x16x32_bf16 v[58:61], v[188:191], v[106:109], v[34:37]
	v_mfma_f32_16x16x32_bf16 v[34:37], v[192:195], v[102:105], v[42:45]
	v_mfma_f32_16x16x32_bf16 v[54:57], v[226:229], v[106:109], v[34:37]
	v_mfma_f32_16x16x32_bf16 v[34:37], v[164:167], v[110:113], v[46:49]
	v_mfma_f32_16x16x32_bf16 v[46:49], v[188:191], v[114:117], v[34:37]
	v_mfma_f32_16x16x32_bf16 v[34:37], v[192:195], v[110:113], v[168:171]
	v_mfma_f32_16x16x32_bf16 v[42:45], v[226:229], v[114:117], v[34:37]
	v_mfma_f32_16x16x32_bf16 v[34:37], v[164:167], v[118:121], v[172:175]
	v_mfma_f32_16x16x32_bf16 v[38:41], v[188:191], v[230:233], v[34:37]
	v_mfma_f32_16x16x32_bf16 v[34:37], v[192:195], v[118:121], v[176:179]
	v_mfma_f32_16x16x32_bf16 v[34:37], v[226:229], v[230:233], v[34:37]
	s_setprio 0
	s_barrier
	s_mov_b32 m0, s79
	ds_read_b128 v[90:93], v224 offset:49152
	ds_read_b128 v[94:97], v224 offset:50176
	ds_read_b128 v[168:171], v224 offset:51200
	ds_read_b128 v[172:175], v224 offset:52224
	ds_read_b128 v[176:179], v224 offset:53248
	ds_read_b128 v[200:203], v224 offset:54272
	ds_read_b128 v[230:233], v224 offset:55296
	ds_read_b128 v[234:237], v224 offset:56320
	s_add_u32 s14, s70, 0x4000
	v_lshl_add_u64 v[78:79], s[74:75], 0, v[152:153]
	global_load_lds_dwordx4 v[78:79], off
	v_lshl_add_u64 v[78:79], v[78:79], 0, s[50:51]
	s_mov_b32 m0, s76
	s_addc_u32 s15, s71, 0
	global_load_lds_dwordx4 v[78:79], off
	s_mov_b32 m0, s77
	v_lshl_add_u64 v[78:79], s[14:15], 0, v[152:153]
	global_load_lds_dwordx4 v[78:79], off
	v_lshl_add_u64 v[78:79], v[78:79], 0, s[50:51]
	s_mov_b32 m0, s78
	s_nop 0
	global_load_lds_dwordx4 v[78:79], off
	s_mov_b32 m0, s31
	v_lshl_add_u64 v[78:79], s[72:73], 0, v[152:153]
	global_load_lds_dwordx4 v[78:79], off
	v_lshl_add_u64 v[78:79], v[78:79], 0, s[50:51]
	s_mov_b32 m0, s33
	s_nop 0
	global_load_lds_dwordx4 v[78:79], off
	v_lshlrev_b32_e32 v239, 2, v220
	v_and_b32_e32 v239, -8, v239
	v_add_u32_e32 v239, s34, v239
	s_lshl_b32 s98, s21, 6
	v_add_u32_e32 v241, s98, v239
	v_lshlrev_b32_e32 v240, 1, v239
	v_bfe_u32 v239, v239, 5, 1
	v_and_b32_e32 v240, 48, v240
	v_ashrrev_i32_e32 v241, 6, v241
	v_lshlrev_b32_e32 v243, 5, v220
	v_and_b32_e32 v243, 32, v243
	v_add_u32_e32 v243, v243, v1
	s_add_i32 s98, s20, s28
	v_add_u32_e32 v243, s98, v243
	v_add_u32_e32 v244, 0, v243
	v_lshrrev_b32_e32 v245, 2, v244
	v_lshrrev_b32_e32 v247, 3, v244
	v_lshlrev_b32_e32 v248, 6, v244
	v_lshlrev_b32_e32 v244, 2, v244
	v_and_b32_e32 v245, 0x3ffe0, v245
	v_and_or_b32 v247, v247, 14, v239
	v_and_b32_e32 v248, 0x3c0, v248
	v_and_b32_e32 v244, 32, v244
	v_add_lshl_u32 v245, v245, v241, 14
	v_lshlrev_b32_e32 v247, 10, v247
	v_bitop3_b32 v244, v248, v244, v240 bitop3:0x36
	v_or3_b32 v249, v244, v247, v245
	v_add_u32_e32 v244, 16, v243
	v_lshrrev_b32_e32 v245, 2, v244
	v_lshrrev_b32_e32 v247, 3, v244
	v_lshlrev_b32_e32 v248, 6, v244
	v_lshlrev_b32_e32 v244, 2, v244
	v_and_b32_e32 v245, 0x3ffe0, v245
	v_and_or_b32 v247, v247, 14, v239
	v_and_b32_e32 v248, 0x3c0, v248
	v_and_b32_e32 v244, 32, v244
	v_add_lshl_u32 v245, v245, v241, 14
	v_lshlrev_b32_e32 v247, 10, v247
	v_bitop3_b32 v244, v248, v244, v240 bitop3:0x36
	v_or3_b32 v251, v244, v247, v245
	v_add_u32_e32 v244, 128, v243
	v_lshrrev_b32_e32 v245, 2, v244
	v_lshrrev_b32_e32 v247, 3, v244
	v_lshlrev_b32_e32 v248, 6, v244
	v_lshlrev_b32_e32 v244, 2, v244
	v_and_b32_e32 v245, 0x3ffe0, v245
	v_and_or_b32 v247, v247, 14, v239
	v_and_b32_e32 v248, 0x3c0, v248
	v_and_b32_e32 v244, 32, v244
	v_add_lshl_u32 v245, v245, v241, 14
	v_lshlrev_b32_e32 v247, 10, v247
	v_bitop3_b32 v244, v248, v244, v240 bitop3:0x36
	v_or3_b32 v252, v244, v247, v245
	v_add_u32_e32 v244, 144, v243
	v_lshrrev_b32_e32 v245, 2, v244
	v_lshrrev_b32_e32 v247, 3, v244
	v_lshlrev_b32_e32 v248, 6, v244
	v_lshlrev_b32_e32 v244, 2, v244
	v_and_b32_e32 v245, 0x3ffe0, v245
	v_and_or_b32 v247, v247, 14, v239
	v_and_b32_e32 v248, 0x3c0, v248
	v_and_b32_e32 v244, 32, v244
	v_add_lshl_u32 v245, v245, v241, 14
	v_lshlrev_b32_e32 v247, 10, v247
	v_bitop3_b32 v244, v248, v244, v240 bitop3:0x36
	v_or3_b32 v253, v244, v247, v245
	s_waitcnt vmcnt(8)
	s_waitcnt lgkmcnt(0)
	s_barrier
	global_load_dwordx4 v[238:241], v249, s[36:37]
	global_load_dwordx4 v[242:245], v251, s[36:37]
	global_load_dwordx4 v[246:249], v252, s[36:37]
	global_load_dwordx4 v[250:253], v253, s[36:37]
	s_setprio 1
	s_waitcnt lgkmcnt(0)
	v_mfma_f32_16x16x32_bf16 v[78:81], v[18:21], v[90:93], v[130:133]
	v_mfma_f32_16x16x32_bf16 v[118:121], v[22:25], v[94:97], v[78:81]
	v_mfma_f32_16x16x32_bf16 v[78:81], v[26:29], v[90:93], v[134:137]
	v_mfma_f32_16x16x32_bf16 v[114:117], v[30:33], v[94:97], v[78:81]
	v_mfma_f32_16x16x32_bf16 v[78:81], v[18:21], v[168:171], v[138:141]
	v_mfma_f32_16x16x32_bf16 v[110:113], v[22:25], v[172:175], v[78:81]
	v_mfma_f32_16x16x32_bf16 v[78:81], v[26:29], v[168:171], v[196:199]
	v_mfma_f32_16x16x32_bf16 v[106:109], v[30:33], v[172:175], v[78:81]
	v_mfma_f32_16x16x32_bf16 v[78:81], v[18:21], v[176:179], v[204:207]
	v_mfma_f32_16x16x32_bf16 v[2:5], v[18:21], v[230:233], v[2:5]
	v_mfma_f32_16x16x32_bf16 v[102:105], v[22:25], v[200:203], v[78:81]
	v_mfma_f32_16x16x32_bf16 v[78:81], v[26:29], v[176:179], v[156:159]
	v_mfma_f32_16x16x32_bf16 v[82:85], v[22:25], v[234:237], v[2:5]
	v_mfma_f32_16x16x32_bf16 v[2:5], v[26:29], v[230:233], v[6:9]
	v_mfma_f32_16x16x32_bf16 v[98:101], v[30:33], v[200:203], v[78:81]
	v_mfma_f32_16x16x32_bf16 v[78:81], v[30:33], v[234:237], v[2:5]
	s_setprio 0
	s_setprio 1
	v_mfma_f32_16x16x32_bf16 v[2:5], v[164:167], v[90:93], v[10:13]
	v_mfma_f32_16x16x32_bf16 v[30:33], v[188:191], v[94:97], v[2:5]
	v_mfma_f32_16x16x32_bf16 v[2:5], v[192:195], v[90:93], v[14:17]
	v_mfma_f32_16x16x32_bf16 v[26:29], v[226:229], v[94:97], v[2:5]
	v_mfma_f32_16x16x32_bf16 v[2:5], v[164:167], v[168:171], v[208:211]
	v_mfma_f32_16x16x32_bf16 v[22:25], v[188:191], v[172:175], v[2:5]
	v_mfma_f32_16x16x32_bf16 v[2:5], v[192:195], v[168:171], v[212:215]
	v_mfma_f32_16x16x32_bf16 v[18:21], v[226:229], v[172:175], v[2:5]
	v_mfma_f32_16x16x32_bf16 v[2:5], v[164:167], v[176:179], v[216:219]
	v_mfma_f32_16x16x32_bf16 v[14:17], v[188:191], v[200:203], v[2:5]
	v_mfma_f32_16x16x32_bf16 v[2:5], v[192:195], v[176:179], v[180:183]
	v_mfma_f32_16x16x32_bf16 v[10:13], v[226:229], v[200:203], v[2:5]
	v_mfma_f32_16x16x32_bf16 v[2:5], v[164:167], v[230:233], v[184:187]
	v_mfma_f32_16x16x32_bf16 v[6:9], v[188:191], v[234:237], v[2:5]
	v_mfma_f32_16x16x32_bf16 v[2:5], v[192:195], v[230:233], v[160:163]
	v_mfma_f32_16x16x32_bf16 v[2:5], v[226:229], v[234:237], v[2:5]
	s_setprio 0
	s_barrier
	s_andn2_b64 vcc, exec, s[6:7]
	s_cbranch_vccnz .LBB0_863
	s_barrier
.LBB0_863:
	v_mov_b32_e32 v154, v1
	v_mov_b32_e32 v229, v220
	s_lshl_b32 s14, s21, 6
	v_lshlrev_b32_e32 v90, 2, v229
	v_add_u32_e32 v230, s34, v90
	v_and_b32_e32 v90, -8, v90
	v_lshlrev_b32_e32 v91, 5, v229
	v_add_u32_e32 v90, s34, v90
	v_and_b32_e32 v91, 32, v91
	v_add_u32_e32 v156, s14, v230
	v_add_u32_e32 v228, s14, v90
	v_add_u32_e32 v91, v91, v154
	v_bfe_u32 v226, v90, 5, 1
	v_lshlrev_b32_e32 v90, 1, v90
	s_add_i32 s14, s20, s28
	v_and_b32_e32 v225, 48, v90
	v_add_u32_e32 v90, s14, v91
	v_lshrrev_b32_e32 v92, 2, v90
	v_lshrrev_b32_e32 v93, 3, v90
	v_lshlrev_b32_e32 v95, 6, v90
	v_lshlrev_b32_e32 v90, 2, v90
	v_ashrrev_i32_e32 v227, 6, v228
	v_and_b32_e32 v92, 0x3ffe0, v92
	v_and_or_b32 v93, v93, 14, v226
	v_and_b32_e32 v95, 0x3c0, v95
	v_and_b32_e32 v90, 32, v90
	v_add_u32_e32 v94, 16, v91
	v_add_lshl_u32 v92, v92, v227, 14
	v_lshlrev_b32_e32 v93, 10, v93
	v_bitop3_b32 v90, v95, v90, v225 bitop3:0x36
	v_or3_b32 v90, v90, v93, v92
	v_add_u32_e32 v92, s14, v94
	v_lshrrev_b32_e32 v93, 2, v92
	v_lshrrev_b32_e32 v95, 3, v92
	v_lshlrev_b32_e32 v96, 6, v92
	v_lshlrev_b32_e32 v92, 2, v92
	v_and_b32_e32 v93, 0x3ffe0, v93
	v_and_or_b32 v95, v95, 14, v226
	v_and_b32_e32 v96, 0x3c0, v96
	v_and_b32_e32 v92, 32, v92
	v_add_lshl_u32 v93, v93, v227, 14
	v_lshlrev_b32_e32 v95, 10, v95
	v_bitop3_b32 v92, v96, v92, v225 bitop3:0x36
	s_addk_i32 s14, 0x80
	v_or3_b32 v92, v92, v95, v93
	s_nop 0
	s_nop 0
	v_add_u32_e32 v90, s14, v91
	v_lshrrev_b32_e32 v91, 2, v90
	v_lshrrev_b32_e32 v92, 3, v90
	v_lshlrev_b32_e32 v93, 6, v90
	v_lshlrev_b32_e32 v90, 2, v90
	v_ashrrev_i32_e32 v157, 31, v156
	v_and_b32_e32 v91, 0x3ffe0, v91
	v_and_or_b32 v92, v92, 14, v226
	v_and_b32_e32 v93, 0x3c0, v93
	v_and_b32_e32 v90, 32, v90
	v_lshlrev_b64 v[150:151], 2, v[156:157]
	v_add_lshl_u32 v91, v91, v227, 14
	v_lshlrev_b32_e32 v92, 10, v92
	v_bitop3_b32 v90, v93, v90, v225 bitop3:0x36
	v_lshl_add_u64 v[162:163], s[44:45], 0, v[150:151]
	v_or3_b32 v90, v90, v92, v91
	global_load_dwordx4 v[158:161], v[162:163], off
	v_add_u32_e32 v94, s14, v94
	s_nop 0
	v_lshl_add_u64 v[164:165], s[42:43], 0, v[150:151]
	v_lshrrev_b32_e32 v95, 2, v94
	v_lshrrev_b32_e32 v96, 3, v94
	v_lshlrev_b32_e32 v97, 6, v94
	v_lshlrev_b32_e32 v94, 2, v94
	global_load_dwordx4 v[168:171], v[164:165], off
	v_and_b32_e32 v95, 0x3ffe0, v95
	v_and_or_b32 v96, v96, 14, v226
	v_and_b32_e32 v97, 0x3c0, v97
	v_and_b32_e32 v94, 32, v94
	v_add_lshl_u32 v95, v95, v227, 14
	v_lshlrev_b32_e32 v96, 10, v96
	v_bitop3_b32 v94, v97, v94, v225 bitop3:0x36
	v_or3_b32 v94, v94, v96, v95
	s_nop 0
	v_readlane_b32 s14, v255, 8
	v_readlane_b32 s15, v255, 9
	s_nop 1
	v_lshl_add_u64 v[166:167], s[14:15], 0, v[150:151]
	global_load_dwordx4 v[130:133], v[166:167], off
	s_waitcnt vmcnt(0)
	v_mov_b32_e32 v138, v238
	v_mov_b32_e32 v139, v239
	v_mov_b32_e32 v140, v240
	v_mov_b32_e32 v141, v241
	v_mov_b32_e32 v134, v242
	v_mov_b32_e32 v135, v243
	v_mov_b32_e32 v136, v244
	v_mov_b32_e32 v137, v245
	v_mov_b32_e32 v90, v246
	v_mov_b32_e32 v91, v247
	v_mov_b32_e32 v92, v248
	v_mov_b32_e32 v93, v249
	v_mov_b32_e32 v94, v250
	v_mov_b32_e32 v95, v251
	v_mov_b32_e32 v96, v252
	v_mov_b32_e32 v97, v253
	v_mov_b32_e32 v186, v140
	v_mov_b32_e32 v187, v141
	v_mov_b32_e32 v190, v136
	v_mov_b32_e32 v191, v137
	v_permlane16_swap_b32_e32 v138, v186
	v_permlane16_swap_b32_e32 v139, v187
	v_permlane16_swap_b32_e32 v134, v190
	v_permlane16_swap_b32_e32 v135, v191
	v_mul_f32_e32 v178, 0xbfb8aa3b, v158
	v_mul_f32_e32 v180, 0xbfb8aa3b, v160
	v_mov_b32_e32 v212, v92
	v_fmamk_f32 v92, v142, 0xbfb8aa3b, v178
	v_fmamk_f32 v140, v144, 0xbfb8aa3b, v180
	v_mov_b32_e32 v214, v93
	v_exp_f32_e32 v93, v92
	v_exp_f32_e32 v141, v140
	v_mul_f32_e32 v179, 0xbfb8aa3b, v168
	v_fmamk_f32 v92, v146, 0xbfb8aa3b, v179
	v_mul_f32_e32 v146, 0xbfb8aa3b, v169
	v_mul_f32_e32 v181, 0xbfb8aa3b, v170
	v_mul_f32_e32 v184, 0xbfb8aa3b, v171
	v_add_f32_e32 v136, 1.0, v93
	v_fmamk_f32 v93, v147, 0xbfb8aa3b, v146
	v_fmamk_f32 v140, v148, 0xbfb8aa3b, v181
	v_add_f32_e32 v144, 1.0, v141
	v_fmamk_f32 v141, v149, 0xbfb8aa3b, v184
	v_exp_f32_e32 v92, v92
	v_exp_f32_e32 v93, v93
	v_mul_f32_e32 v147, 0xbfb8aa3b, v159
	v_exp_f32_e32 v140, v140
	v_exp_f32_e32 v141, v141
	v_mul_f32_e32 v185, 0xbfb8aa3b, v161
	v_mov_b32_e32 v213, v96
	v_fmamk_f32 v96, v143, 0xbfb8aa3b, v147
	v_fmamk_f32 v142, v145, 0xbfb8aa3b, v185
	v_mov_b32_e32 v215, v97
	v_exp_f32_e32 v97, v96
	v_exp_f32_e32 v143, v142
	v_pk_add_f32 v[92:93], v[92:93], 1.0 op_sel_hi:[1,0]
	v_pk_add_f32 v[140:141], v[140:141], 1.0 op_sel_hi:[1,0]
	v_mul_f32_e32 v96, v92, v136
	v_mul_f32_e32 v142, v140, v144
	v_rcp_f32_e32 v96, v96
	v_add_f32_e32 v137, 1.0, v97
	v_rcp_f32_e32 v142, v142
	v_add_f32_e32 v145, 1.0, v143
	v_mul_f32_e32 v97, v93, v137
	v_mul_f32_e32 v143, v141, v145
	v_rcp_f32_e32 v97, v97
	v_rcp_f32_e32 v143, v143
	v_mul_f32_e32 v136, v136, v96
	v_mul_f32_e32 v144, v144, v142
	v_pk_mul_f32 v[92:93], v[92:93], v[96:97]
	v_pk_mul_f32 v[140:141], v[140:141], v[142:143]
	v_permlane16_swap_b32_e32 v90, v212
	v_permlane16_swap_b32_e32 v91, v214
	v_permlane16_swap_b32_e32 v94, v213
	v_permlane16_swap_b32_e32 v95, v215
	s_waitcnt vmcnt(0)
	v_mul_f32_e32 v136, v130, v136
	v_mul_f32_e32 v144, v132, v144
	v_exp_f32_e32 v158, v136
	v_mul_f32_e32 v136, v137, v97
	v_exp_f32_e32 v160, v144
	v_mul_f32_e32 v144, v145, v143
	v_mul_f32_e32 v136, v131, v136
	v_mul_f32_e32 v144, v133, v144
	v_exp_f32_e32 v159, v136
	v_exp_f32_e32 v161, v144
	v_fma_f32 v136, -v158, v158, 1.0
	v_fma_f32 v144, -v160, v160, 1.0
	v_fma_f32 v137, -v159, v159, 1.0
	v_fma_f32 v145, -v161, v161, 1.0
	v_sqrt_f32_e32 v136, v136
	v_sqrt_f32_e32 v137, v137
	v_sqrt_f32_e32 v144, v144
	v_sqrt_f32_e32 v145, v145
	v_pk_mul_f32 v[96:97], v[92:93], v[136:137]
	v_pk_mul_f32 v[136:137], v[140:141], v[144:145]
	v_fmamk_f32 v93, v122, 0xbfb8aa3b, v178
	v_fmamk_f32 v124, v124, 0xbfb8aa3b, v180
	v_exp_f32_e32 v122, v93
	v_exp_f32_e32 v124, v124
	v_fmamk_f32 v128, v128, 0xbfb8aa3b, v181
	v_fmamk_f32 v129, v129, 0xbfb8aa3b, v184
	v_fmamk_f32 v92, v126, 0xbfb8aa3b, v179
	v_fmamk_f32 v93, v127, 0xbfb8aa3b, v146
	v_exp_f32_e32 v128, v128
	v_exp_f32_e32 v129, v129
	v_exp_f32_e32 v92, v92
	v_exp_f32_e32 v93, v93
	v_add_f32_e32 v140, 1.0, v122
	v_fmamk_f32 v122, v123, 0xbfb8aa3b, v147
	v_add_f32_e32 v142, 1.0, v124
	v_fmamk_f32 v124, v125, 0xbfb8aa3b, v185
	v_exp_f32_e32 v127, v122
	v_exp_f32_e32 v143, v124
	v_pk_add_f32 v[124:125], v[128:129], 1.0 op_sel_hi:[1,0]
	v_pk_add_f32 v[122:123], v[92:93], 1.0 op_sel_hi:[1,0]
	v_mul_f32_e32 v128, v124, v142
	v_mul_f32_e32 v92, v122, v140
	v_add_f32_e32 v93, 1.0, v127
	v_rcp_f32_e32 v128, v128
	v_add_f32_e32 v143, 1.0, v143
	v_rcp_f32_e32 v126, v92
	v_mul_f32_e32 v92, v123, v93
	v_mul_f32_e32 v129, v125, v143
	v_rcp_f32_e32 v127, v92
	v_rcp_f32_e32 v129, v129
	v_mul_f32_e32 v142, v142, v128
	v_mul_f32_e32 v142, v132, v142
	v_mul_f32_e32 v92, v140, v126
	v_mul_f32_e32 v93, v93, v127
	v_exp_f32_e32 v148, v142
	v_mul_f32_e32 v142, v143, v129
	v_mul_f32_e32 v92, v130, v92
	v_mul_f32_e32 v93, v131, v93
	v_mul_f32_e32 v142, v133, v142
	v_exp_f32_e32 v92, v92
	v_exp_f32_e32 v93, v93
	v_exp_f32_e32 v149, v142
	v_fma_f32 v142, -v148, v148, 1.0
	v_fma_f32 v140, -v92, v92, 1.0
	v_fma_f32 v141, -v93, v93, 1.0
	v_fma_f32 v143, -v149, v149, 1.0
	v_sqrt_f32_e32 v140, v140
	v_sqrt_f32_e32 v141, v141
	v_sqrt_f32_e32 v142, v142
	v_sqrt_f32_e32 v143, v143
	v_pk_mul_f32 v[122:123], v[122:123], v[126:127]
	v_pk_mul_f32 v[124:125], v[124:125], v[128:129]
	v_pk_mul_f32 v[168:169], v[122:123], v[140:141]
	v_pk_mul_f32 v[170:171], v[124:125], v[142:143]
	v_fmamk_f32 v74, v74, 0xbfb8aa3b, v178
	v_fmamk_f32 v76, v76, 0xbfb8aa3b, v180
	v_exp_f32_e32 v74, v74
	v_exp_f32_e32 v76, v76
	v_fmamk_f32 v86, v86, 0xbfb8aa3b, v179
	v_fmamk_f32 v87, v87, 0xbfb8aa3b, v146
	v_fmamk_f32 v88, v88, 0xbfb8aa3b, v181
	v_fmamk_f32 v89, v89, 0xbfb8aa3b, v184
	v_exp_f32_e32 v86, v86
	v_exp_f32_e32 v87, v87
	v_exp_f32_e32 v88, v88
	v_exp_f32_e32 v89, v89
	v_add_f32_e32 v122, 1.0, v74
	v_fmamk_f32 v74, v75, 0xbfb8aa3b, v147
	v_add_f32_e32 v124, 1.0, v76
	v_fmamk_f32 v76, v77, 0xbfb8aa3b, v185
	v_exp_f32_e32 v123, v74
	v_exp_f32_e32 v125, v76
	v_pk_add_f32 v[74:75], v[86:87], 1.0 op_sel_hi:[1,0]
	v_pk_add_f32 v[76:77], v[88:89], 1.0 op_sel_hi:[1,0]
	v_mul_f32_e32 v86, v74, v122
	v_mul_f32_e32 v88, v76, v124
	v_rcp_f32_e32 v86, v86
	v_add_f32_e32 v123, 1.0, v123
	v_rcp_f32_e32 v88, v88
	v_add_f32_e32 v125, 1.0, v125
	v_mul_f32_e32 v87, v75, v123
	v_mul_f32_e32 v89, v77, v125
	v_rcp_f32_e32 v87, v87
	v_rcp_f32_e32 v89, v89
	v_mul_f32_e32 v122, v122, v86
	v_mul_f32_e32 v124, v124, v88
	v_mul_f32_e32 v122, v130, v122
	v_mul_f32_e32 v124, v132, v124
	v_exp_f32_e32 v172, v122
	v_mul_f32_e32 v122, v123, v87
	v_exp_f32_e32 v182, v124
	v_mul_f32_e32 v124, v125, v89
	v_mul_f32_e32 v122, v131, v122
	v_mul_f32_e32 v124, v133, v124
	v_exp_f32_e32 v173, v122
	v_exp_f32_e32 v183, v124
	v_fma_f32 v122, -v172, v172, 1.0
	v_fma_f32 v124, -v182, v182, 1.0
	v_fma_f32 v123, -v173, v173, 1.0
	v_fma_f32 v125, -v183, v183, 1.0
	v_sqrt_f32_e32 v122, v122
	v_sqrt_f32_e32 v123, v123
	v_sqrt_f32_e32 v124, v124
	v_sqrt_f32_e32 v125, v125
	v_pk_mul_f32 v[74:75], v[74:75], v[86:87]
	v_pk_mul_f32 v[76:77], v[76:77], v[88:89]
	v_pk_mul_f32 v[174:175], v[74:75], v[122:123]
	v_pk_mul_f32 v[176:177], v[76:77], v[124:125]
	v_fmac_f32_e32 v179, 0xbfb8aa3b, v70
	v_fmac_f32_e32 v178, 0xbfb8aa3b, v50
	v_fmac_f32_e32 v146, 0xbfb8aa3b, v71
	v_fmac_f32_e32 v181, 0xbfb8aa3b, v72
	v_fmac_f32_e32 v180, 0xbfb8aa3b, v52
	v_fmac_f32_e32 v184, 0xbfb8aa3b, v73
	v_exp_f32_e32 v50, v178
	v_exp_f32_e32 v70, v179
	v_exp_f32_e32 v71, v146
	v_exp_f32_e32 v52, v180
	v_exp_f32_e32 v72, v181
	v_exp_f32_e32 v73, v184
	v_fmac_f32_e32 v147, 0xbfb8aa3b, v51
	v_fmac_f32_e32 v185, 0xbfb8aa3b, v53
	v_exp_f32_e32 v75, v147
	v_exp_f32_e32 v77, v185
	v_add_f32_e32 v74, 1.0, v50
	v_pk_add_f32 v[50:51], v[70:71], 1.0 op_sel_hi:[1,0]
	v_add_f32_e32 v76, 1.0, v52
	v_pk_add_f32 v[52:53], v[72:73], 1.0 op_sel_hi:[1,0]
	v_mul_f32_e32 v70, v50, v74
	v_mul_f32_e32 v72, v52, v76
	v_rcp_f32_e32 v70, v70
	v_add_f32_e32 v75, 1.0, v75
	v_rcp_f32_e32 v72, v72
	v_add_f32_e32 v77, 1.0, v77
	v_mul_f32_e32 v71, v51, v75
	v_mul_f32_e32 v73, v53, v77
	v_rcp_f32_e32 v71, v71
	v_rcp_f32_e32 v73, v73
	v_mul_f32_e32 v74, v74, v70
	v_mul_f32_e32 v76, v76, v72
	v_mul_f32_e32 v74, v130, v74
	v_mul_f32_e32 v76, v132, v76
	v_exp_f32_e32 v178, v74
	v_mul_f32_e32 v74, v75, v71
	v_exp_f32_e32 v188, v76
	v_mul_f32_e32 v76, v77, v73
	v_mul_f32_e32 v74, v131, v74
	v_mul_f32_e32 v76, v133, v76
	v_exp_f32_e32 v179, v74
	v_exp_f32_e32 v189, v76
	v_fma_f32 v74, -v178, v178, 1.0
	v_fma_f32 v76, -v188, v188, 1.0
	v_fma_f32 v75, -v179, v179, 1.0
	v_fma_f32 v77, -v189, v189, 1.0
	v_sqrt_f32_e32 v74, v74
	v_sqrt_f32_e32 v75, v75
	v_sqrt_f32_e32 v76, v76
	v_sqrt_f32_e32 v77, v77
	v_pk_mul_f32 v[50:51], v[50:51], v[70:71]
	v_pk_mul_f32 v[52:53], v[52:53], v[72:73]
	v_pk_mul_f32 v[180:181], v[50:51], v[74:75]
	v_pk_mul_f32 v[184:185], v[52:53], v[76:77]
	global_load_dwordx4 v[144:147], v[164:165], off
	global_load_dwordx4 v[140:143], v[162:163], off
	global_load_dwordx4 v[130:133], v[166:167], off
	v_lshl_add_u64 v[50:51], s[56:57], 0, v[150:151]
	v_lshl_add_u64 v[52:53], s[60:61], 0, v[150:151]
	v_lshl_add_u64 v[150:151], s[62:63], 0, v[150:151]
	global_load_dwordx4 v[126:129], v[50:51], off
	global_load_dwordx4 v[122:125], v[52:53], off
	global_load_dwordx4 v[86:89], v[150:151], off
	global_load_dwordx4 v[74:77], v[50:51], off
	global_load_dwordx4 v[70:73], v[52:53], off
	s_nop 0
	global_load_dwordx4 v[50:53], v[150:151], off
	v_lshlrev_b32_e32 v196, 16, v138
	v_and_b32_e32 v197, 0xffff0000, v138
	v_lshlrev_b32_e32 v200, 16, v134
	v_and_b32_e32 v201, 0xffff0000, v134
	v_lshlrev_b32_e32 v198, 16, v139
	v_and_b32_e32 v199, 0xffff0000, v139
	v_pk_mul_f32 v[138:139], v[96:97], v[196:197]
	v_lshlrev_b32_e32 v202, 16, v135
	v_and_b32_e32 v203, 0xffff0000, v135
	v_pk_mul_f32 v[134:135], v[168:169], v[200:201]
	v_lshlrev_b32_e32 v204, 16, v186
	v_and_b32_e32 v205, 0xffff0000, v186
	v_pk_mul_f32 v[162:163], v[136:137], v[198:199]
	v_pk_mul_f32 v[96:97], v[170:171], v[202:203]
	v_lshlrev_b32_e32 v206, 16, v187
	v_and_b32_e32 v207, 0xffff0000, v187
	v_pk_mul_f32 v[150:151], v[174:175], v[204:205]
	v_lshlrev_b32_e32 v208, 16, v190
	v_and_b32_e32 v209, 0xffff0000, v190
	v_pk_fma_f32 v[168:169], v[92:93], v[138:139], v[134:135]
	v_pk_mul_f32 v[174:175], v[92:93], v[158:159]
	v_pk_mul_f32 v[136:137], v[176:177], v[206:207]
	v_lshlrev_b32_e32 v210, 16, v191
	v_and_b32_e32 v211, 0xffff0000, v191
	v_pk_mul_f32 v[164:165], v[180:181], v[208:209]
	v_pk_fma_f32 v[166:167], v[172:173], v[168:169], v[150:151]
	v_pk_mul_f32 v[172:173], v[172:173], v[174:175]
	v_pk_fma_f32 v[180:181], v[148:149], v[162:163], v[96:97]
	v_pk_mul_f32 v[186:187], v[148:149], v[160:161]
	v_pk_mul_f32 v[176:177], v[184:185], v[210:211]
	v_pk_fma_f32 v[164:165], v[178:179], v[166:167], v[164:165]
	v_pk_mul_f32 v[170:171], v[178:179], v[172:173]
	v_pk_fma_f32 v[178:179], v[182:183], v[180:181], v[136:137]
	v_pk_mul_f32 v[184:185], v[182:183], v[186:187]
	v_pk_fma_f32 v[176:177], v[188:189], v[178:179], v[176:177]
	v_pk_mul_f32 v[182:183], v[188:189], v[184:185]
	v_mov_b32_e32 v92, v164
	v_mov_b32_e32 v93, v183
	v_mov_b32_e32 v96, v176
	v_mov_b32_e32 v97, v170
	v_mov_b32_e32 v148, v182
	v_mov_b32_e32 v137, v165
	v_mov_b32_e32 v151, v177
	v_mov_b32_e32 v136, v171
	s_nop 1
	v_fmac_f32_dpp v92, v92, v97 row_shr:1 row_mask:0xf bank_mask:0xf
	v_fmac_f32_dpp v137, v137, v136 row_shr:1 row_mask:0xf bank_mask:0xf
	v_fmac_f32_dpp v96, v96, v148 row_shr:1 row_mask:0xf bank_mask:0xf
	v_fmac_f32_dpp v151, v151, v93 row_shr:1 row_mask:0xf bank_mask:0xf
	v_mul_f32_dpp v97, v97, v97 row_shr:1 row_mask:0xf bank_mask:0xf
	v_mul_f32_dpp v136, v136, v136 row_shr:1 row_mask:0xf bank_mask:0xf
	v_mul_f32_dpp v148, v148, v148 row_shr:1 row_mask:0xf bank_mask:0xf
	v_mul_f32_dpp v93, v93, v93 row_shr:1 row_mask:0xf bank_mask:0xf
	v_fmac_f32_dpp v92, v92, v97 row_shr:2 row_mask:0xf bank_mask:0xf
	v_fmac_f32_dpp v137, v137, v136 row_shr:2 row_mask:0xf bank_mask:0xf
	v_fmac_f32_dpp v96, v96, v148 row_shr:2 row_mask:0xf bank_mask:0xf
	v_fmac_f32_dpp v151, v151, v93 row_shr:2 row_mask:0xf bank_mask:0xf
	v_mul_f32_dpp v97, v97, v97 row_shr:2 row_mask:0xf bank_mask:0xf
	v_mul_f32_dpp v136, v136, v136 row_shr:2 row_mask:0xf bank_mask:0xf
	v_mul_f32_dpp v148, v148, v148 row_shr:2 row_mask:0xf bank_mask:0xf
	v_mul_f32_dpp v93, v93, v93 row_shr:2 row_mask:0xf bank_mask:0xf
	v_fmac_f32_dpp v92, v92, v97 row_shr:4 row_mask:0xf bank_mask:0xf
	v_fmac_f32_dpp v137, v137, v136 row_shr:4 row_mask:0xf bank_mask:0xf
	v_fmac_f32_dpp v96, v96, v148 row_shr:4 row_mask:0xf bank_mask:0xf
	v_fmac_f32_dpp v151, v151, v93 row_shr:4 row_mask:0xf bank_mask:0xf
	v_mul_f32_dpp v97, v97, v97 row_shr:4 row_mask:0xf bank_mask:0xf
	v_mul_f32_dpp v136, v136, v136 row_shr:4 row_mask:0xf bank_mask:0xf
	v_mul_f32_dpp v148, v148, v148 row_shr:4 row_mask:0xf bank_mask:0xf
	v_mul_f32_dpp v93, v93, v93 row_shr:4 row_mask:0xf bank_mask:0xf
	v_fmac_f32_dpp v92, v92, v97 row_shr:8 row_mask:0xf bank_mask:0xf
	v_fmac_f32_dpp v137, v137, v136 row_shr:8 row_mask:0xf bank_mask:0xf
	v_fmac_f32_dpp v96, v96, v148 row_shr:8 row_mask:0xf bank_mask:0xf
	v_fmac_f32_dpp v151, v151, v93 row_shr:8 row_mask:0xf bank_mask:0xf
	v_mul_f32_dpp v97, v97, v97 row_shr:8 row_mask:0xf bank_mask:0xf
	v_mul_f32_dpp v136, v136, v136 row_shr:8 row_mask:0xf bank_mask:0xf
	v_mul_f32_dpp v148, v148, v148 row_shr:8 row_mask:0xf bank_mask:0xf
	v_mul_f32_dpp v93, v93, v93 row_shr:8 row_mask:0xf bank_mask:0xf
	s_nop 1
	v_mov_b32_e32 v188, 1.0
	v_mov_b32_e32 v189, 1.0
	v_mov_b32_e32 v192, 1.0
	v_mov_b32_e32 v193, 1.0
	v_mov_b32_dpp v188, v97 row_shr:1 row_mask:0xf bank_mask:0xf
	v_mov_b32_dpp v190, v92 row_shr:1 row_mask:0xf bank_mask:0xf bound_ctrl:1
	v_mov_b32_dpp v134, v97 row_newbcast:15 row_mask:0xf bank_mask:0xf bound_ctrl:1
	v_mov_b32_dpp v135, v92 row_newbcast:15 row_mask:0xf bank_mask:0xf bound_ctrl:1
	v_mov_b32_dpp v189, v136 row_shr:1 row_mask:0xf bank_mask:0xf
	v_mov_b32_dpp v191, v137 row_shr:1 row_mask:0xf bank_mask:0xf bound_ctrl:1
	v_mov_b32_dpp v136, v136 row_newbcast:15 row_mask:0xf bank_mask:0xf bound_ctrl:1
	v_mov_b32_dpp v137, v137 row_newbcast:15 row_mask:0xf bank_mask:0xf bound_ctrl:1
	v_mov_b32_dpp v192, v148 row_shr:1 row_mask:0xf bank_mask:0xf
	v_mov_b32_dpp v194, v96 row_shr:1 row_mask:0xf bank_mask:0xf bound_ctrl:1
	v_mov_b32_dpp v148, v148 row_newbcast:15 row_mask:0xf bank_mask:0xf bound_ctrl:1
	v_mov_b32_dpp v149, v96 row_newbcast:15 row_mask:0xf bank_mask:0xf bound_ctrl:1
	v_mov_b32_dpp v193, v93 row_shr:1 row_mask:0xf bank_mask:0xf
	v_mov_b32_dpp v195, v151 row_shr:1 row_mask:0xf bank_mask:0xf bound_ctrl:1
	v_mov_b32_dpp v150, v93 row_newbcast:15 row_mask:0xf bank_mask:0xf bound_ctrl:1
	v_mov_b32_dpp v151, v151 row_newbcast:15 row_mask:0xf bank_mask:0xf bound_ctrl:1
	v_cmp_eq_u32_e32 vcc, 0, v154
	s_and_saveexec_b64 s[14:15], vcc
	s_cbranch_execz .LBB0_865
	v_add_u32_e32 v92, s28, v230
	v_lshl_add_u32 v92, v92, 3, 0
	v_add_u32_e32 v92, 0x20200, v92
	ds_write_b128 v92, v[134:137]
	ds_write_b128 v92, v[148:151] offset:16
